# v087 + UP K-loop LDS-DMA rebalance 2/6/2/6 -> 4/4/4/4 pieces per sub-phase (waits 8,6,8,6)
# speedup vs baseline: 1.0008x; 1.0008x over previous
.LBB0_1328:
	s_add_u32 s44, s42, 0xfffc0080
	s_addc_u32 s45, s43, -1
	s_add_i32 s53, 0, 0x10000
	s_cmp_eq_u32 s52, 12
	s_cselect_b32 s47, s1, s45
	s_cselect_b32 s46, s41, s44
	s_cselect_b32 s45, s48, s51
	s_cselect_b32 s44, s49, s50
	s_add_i32 s56, 0, 0x14000
	v_add_u32_e32 v94, s53, v186
	v_add_u32_e32 v174, s56, v186
	ds_read_b128 v[82:85], v94
	ds_read_b128 v[86:89], v94 offset:1024
	ds_read_b128 v[90:93], v94 offset:2048
	ds_read_b128 v[94:97], v94 offset:3072
	ds_read_b128 v[162:165], v174
	ds_read_b128 v[166:169], v174 offset:1024
	ds_read_b128 v[170:173], v174 offset:2048
	ds_read_b128 v[174:177], v174 offset:3072
	s_add_u32 s100, s42, 0xfffc0000
	s_addc_u32 s101, s43, -1
	v_lshl_add_u64 v[198:199], s[100:101], 0, v[148:149]
	s_mov_b32 m0, s33
	s_nop 0
	global_load_lds_dwordx4 v[198:199], off
	v_lshl_add_u64 v[198:199], s[100:101], 0, v[150:151]
	s_mov_b32 m0, s14
	s_nop 0
	global_load_lds_dwordx4 v[198:199], off
	v_lshl_add_u64 v[198:199], s[42:43], 0, v[158:159]
	s_add_i32 m0, s2, 0xc000
	ds_read_b128 v[178:181], v187
	ds_read_b128 v[182:185], v187 offset:1024
	ds_read_b128 v[190:193], v187 offset:2048
	ds_read_b128 v[194:197], v187 offset:3072
	ds_read_b128 v[204:207], v187 offset:4096
	ds_read_b128 v[208:211], v187 offset:5120
	ds_read_b128 v[214:217], v187 offset:6144
	ds_read_b128 v[218:221], v187 offset:7168
	global_load_lds_dwordx4 v[198:199], off
	v_lshl_add_u64 v[198:199], s[42:43], 0, v[160:161]
	s_add_i32 m0, s2, 0xe000
	s_nop 0
	global_load_lds_dwordx4 v[198:199], off
	s_waitcnt vmcnt(8)
	s_waitcnt lgkmcnt(0)
	s_barrier
	s_setprio 1
	s_waitcnt lgkmcnt(0)
	v_mfma_f32_16x16x32_bf16 v[144:147], v[82:85], v[178:181], v[144:147]
	v_mfma_f32_16x16x32_bf16 v[140:143], v[90:93], v[178:181], v[140:143]
	v_mfma_f32_16x16x32_bf16 v[128:131], v[82:85], v[190:193], v[128:131]
	v_mfma_f32_16x16x32_bf16 v[124:127], v[90:93], v[190:193], v[124:127]
	v_mfma_f32_16x16x32_bf16 v[112:115], v[82:85], v[204:207], v[112:115]
	v_mfma_f32_16x16x32_bf16 v[108:111], v[90:93], v[204:207], v[108:111]
	v_mfma_f32_16x16x32_bf16 v[78:81], v[82:85], v[214:217], v[78:81]
	v_mfma_f32_16x16x32_bf16 v[74:77], v[90:93], v[214:217], v[74:77]
	v_mfma_f32_16x16x32_bf16 v[144:147], v[86:89], v[182:185], v[144:147]
	v_mfma_f32_16x16x32_bf16 v[140:143], v[94:97], v[182:185], v[140:143]
	v_mfma_f32_16x16x32_bf16 v[128:131], v[86:89], v[194:197], v[128:131]
	v_mfma_f32_16x16x32_bf16 v[124:127], v[94:97], v[194:197], v[124:127]
	v_mfma_f32_16x16x32_bf16 v[112:115], v[86:89], v[208:211], v[112:115]
	v_mfma_f32_16x16x32_bf16 v[108:111], v[94:97], v[208:211], v[108:111]
	v_mfma_f32_16x16x32_bf16 v[78:81], v[86:89], v[218:221], v[78:81]
	v_mfma_f32_16x16x32_bf16 v[74:77], v[94:97], v[218:221], v[74:77]
	s_setprio 0
	s_setprio 1
	v_mfma_f32_16x16x32_bf16 v[136:139], v[162:165], v[178:181], v[136:139]
	v_mfma_f32_16x16x32_bf16 v[132:135], v[170:173], v[178:181], v[132:135]
	v_mfma_f32_16x16x32_bf16 v[120:123], v[162:165], v[190:193], v[120:123]
	v_mfma_f32_16x16x32_bf16 v[116:119], v[170:173], v[190:193], v[116:119]
	v_mfma_f32_16x16x32_bf16 v[104:107], v[162:165], v[204:207], v[104:107]
	v_mfma_f32_16x16x32_bf16 v[100:103], v[170:173], v[204:207], v[100:103]
	v_mfma_f32_16x16x32_bf16 v[70:73], v[162:165], v[214:217], v[70:73]
	v_mfma_f32_16x16x32_bf16 v[66:69], v[170:173], v[214:217], v[66:69]
	v_mfma_f32_16x16x32_bf16 v[136:139], v[166:169], v[182:185], v[136:139]
	v_mfma_f32_16x16x32_bf16 v[132:135], v[174:177], v[182:185], v[132:135]
	v_mfma_f32_16x16x32_bf16 v[120:123], v[166:169], v[194:197], v[120:123]
	v_mfma_f32_16x16x32_bf16 v[116:119], v[174:177], v[194:197], v[116:119]
	v_mfma_f32_16x16x32_bf16 v[104:107], v[166:169], v[208:211], v[104:107]
	v_mfma_f32_16x16x32_bf16 v[100:103], v[174:177], v[208:211], v[100:103]
	v_mfma_f32_16x16x32_bf16 v[70:73], v[166:169], v[218:221], v[70:73]
	v_mfma_f32_16x16x32_bf16 v[66:69], v[174:177], v[218:221], v[66:69]
	s_setprio 0
	s_barrier
	s_add_i32 s53, s53, s9
	v_lshl_add_u64 v[198:199], s[44:45], 0, v[98:99]
	s_mov_b32 m0, s53
	ds_read_b128 v[178:181], v187 offset:16384
	ds_read_b128 v[182:185], v187 offset:17408
	ds_read_b128 v[190:193], v187 offset:18432
	ds_read_b128 v[194:197], v187 offset:19456
	ds_read_b128 v[204:207], v187 offset:20480
	ds_read_b128 v[208:211], v187 offset:21504
	ds_read_b128 v[214:217], v187 offset:22528
	ds_read_b128 v[218:221], v187 offset:23552
	global_load_lds_dwordx4 v[198:199], off
	s_add_i32 m0, s53, 0x2000
	s_add_u32 s54, s44, 0x40000
	v_lshl_add_u64 v[222:223], s[44:45], 0, v[152:153]
	s_addc_u32 s55, s45, 0
	s_add_i32 s53, s56, s9
	global_load_lds_dwordx4 v[222:223], off
	v_lshl_add_u64 v[224:225], s[54:55], 0, v[98:99]
	s_mov_b32 m0, s53
	s_nop 0
	global_load_lds_dwordx4 v[224:225], off
	v_lshl_add_u64 v[224:225], s[54:55], 0, v[152:153]
	s_add_i32 m0, s53, 0x2000
	s_nop 0
	global_load_lds_dwordx4 v[224:225], off
	s_waitcnt vmcnt(6)
	s_waitcnt lgkmcnt(0)
	s_barrier
	s_setprio 1
	s_waitcnt lgkmcnt(0)
	v_mfma_f32_16x16x32_bf16 v[62:65], v[82:85], v[178:181], v[62:65]
	v_mfma_f32_16x16x32_bf16 v[58:61], v[90:93], v[178:181], v[58:61]
	v_mfma_f32_16x16x32_bf16 v[46:49], v[82:85], v[190:193], v[46:49]
	v_mfma_f32_16x16x32_bf16 v[42:45], v[90:93], v[190:193], v[42:45]
	v_mfma_f32_16x16x32_bf16 v[30:33], v[82:85], v[204:207], v[30:33]
	v_mfma_f32_16x16x32_bf16 v[26:29], v[90:93], v[204:207], v[26:29]
	v_mfma_f32_16x16x32_bf16 v[14:17], v[82:85], v[214:217], v[14:17]
	v_mfma_f32_16x16x32_bf16 v[10:13], v[90:93], v[214:217], v[10:13]
	v_mfma_f32_16x16x32_bf16 v[62:65], v[86:89], v[182:185], v[62:65]
	v_mfma_f32_16x16x32_bf16 v[58:61], v[94:97], v[182:185], v[58:61]
	v_mfma_f32_16x16x32_bf16 v[46:49], v[86:89], v[194:197], v[46:49]
	v_mfma_f32_16x16x32_bf16 v[42:45], v[94:97], v[194:197], v[42:45]
	v_mfma_f32_16x16x32_bf16 v[30:33], v[86:89], v[208:211], v[30:33]
	v_mfma_f32_16x16x32_bf16 v[26:29], v[94:97], v[208:211], v[26:29]
	v_mfma_f32_16x16x32_bf16 v[14:17], v[86:89], v[218:221], v[14:17]
	v_mfma_f32_16x16x32_bf16 v[10:13], v[94:97], v[218:221], v[10:13]
	s_setprio 0
	s_setprio 1
	v_mfma_f32_16x16x32_bf16 v[54:57], v[162:165], v[178:181], v[54:57]
	v_mfma_f32_16x16x32_bf16 v[50:53], v[170:173], v[178:181], v[50:53]
	v_mfma_f32_16x16x32_bf16 v[38:41], v[162:165], v[190:193], v[38:41]
	v_mfma_f32_16x16x32_bf16 v[34:37], v[170:173], v[190:193], v[34:37]
	v_mfma_f32_16x16x32_bf16 v[22:25], v[162:165], v[204:207], v[22:25]
	v_mfma_f32_16x16x32_bf16 v[18:21], v[170:173], v[204:207], v[18:21]
	v_mfma_f32_16x16x32_bf16 v[6:9], v[162:165], v[214:217], v[6:9]
	v_mfma_f32_16x16x32_bf16 v[2:5], v[170:173], v[214:217], v[2:5]
	v_mfma_f32_16x16x32_bf16 v[54:57], v[166:169], v[182:185], v[54:57]
	v_mfma_f32_16x16x32_bf16 v[50:53], v[174:177], v[182:185], v[50:53]
	v_mfma_f32_16x16x32_bf16 v[38:41], v[166:169], v[194:197], v[38:41]
	v_mfma_f32_16x16x32_bf16 v[34:37], v[174:177], v[194:197], v[34:37]
	v_mfma_f32_16x16x32_bf16 v[22:25], v[166:169], v[208:211], v[22:25]
	v_mfma_f32_16x16x32_bf16 v[18:21], v[174:177], v[208:211], v[18:21]
	v_mfma_f32_16x16x32_bf16 v[6:9], v[166:169], v[218:221], v[6:9]
	v_mfma_f32_16x16x32_bf16 v[2:5], v[174:177], v[218:221], v[2:5]
	s_setprio 0
	s_barrier
	s_add_i32 s53, 0, 0x18000
	s_add_i32 s54, 0, 0x1c000
	v_add_u32_e32 v94, s53, v186
	v_add_u32_e32 v174, s54, v186
	ds_read_b128 v[82:85], v94
	ds_read_b128 v[86:89], v94 offset:1024
	ds_read_b128 v[90:93], v94 offset:2048
	ds_read_b128 v[94:97], v94 offset:3072
	ds_read_b128 v[162:165], v174
	ds_read_b128 v[166:169], v174 offset:1024
	ds_read_b128 v[170:173], v174 offset:2048
	ds_read_b128 v[174:177], v174 offset:3072
	v_lshl_add_u64 v[224:225], s[46:47], 0, v[148:149]
	s_mov_b32 m0, s2
	v_lshl_add_u64 v[226:227], s[46:47], 0, v[150:151]
	global_load_lds_dwordx4 v[224:225], off
	s_mov_b32 m0, s4
	s_nop 0
	global_load_lds_dwordx4 v[226:227], off
	s_add_u32 s46, s46, 0x40000
	s_addc_u32 s47, s47, 0
	s_mov_b32 m0, s12
	v_lshl_add_u64 v[228:229], s[46:47], 0, v[148:149]
	ds_read_b128 v[178:181], v187 offset:32768
	ds_read_b128 v[182:185], v187 offset:33792
	ds_read_b128 v[190:193], v187 offset:34816
	ds_read_b128 v[194:197], v187 offset:35840
	ds_read_b128 v[204:207], v187 offset:36864
	ds_read_b128 v[208:211], v187 offset:37888
	ds_read_b128 v[214:217], v187 offset:38912
	ds_read_b128 v[218:221], v187 offset:39936
	global_load_lds_dwordx4 v[228:229], off
	v_lshl_add_u64 v[228:229], s[46:47], 0, v[150:151]
	s_mov_b32 m0, s13
	s_nop 0
	global_load_lds_dwordx4 v[228:229], off
	s_waitcnt vmcnt(8)
	s_waitcnt lgkmcnt(0)
	s_barrier
	s_setprio 1
	s_waitcnt lgkmcnt(0)
	v_mfma_f32_16x16x32_bf16 v[144:147], v[82:85], v[178:181], v[144:147]
	v_mfma_f32_16x16x32_bf16 v[140:143], v[90:93], v[178:181], v[140:143]
	v_mfma_f32_16x16x32_bf16 v[128:131], v[82:85], v[190:193], v[128:131]
	v_mfma_f32_16x16x32_bf16 v[124:127], v[90:93], v[190:193], v[124:127]
	v_mfma_f32_16x16x32_bf16 v[112:115], v[82:85], v[204:207], v[112:115]
	v_mfma_f32_16x16x32_bf16 v[108:111], v[90:93], v[204:207], v[108:111]
	v_mfma_f32_16x16x32_bf16 v[78:81], v[82:85], v[214:217], v[78:81]
	v_mfma_f32_16x16x32_bf16 v[74:77], v[90:93], v[214:217], v[74:77]
	v_mfma_f32_16x16x32_bf16 v[144:147], v[86:89], v[182:185], v[144:147]
	v_mfma_f32_16x16x32_bf16 v[140:143], v[94:97], v[182:185], v[140:143]
	v_mfma_f32_16x16x32_bf16 v[128:131], v[86:89], v[194:197], v[128:131]
	v_mfma_f32_16x16x32_bf16 v[124:127], v[94:97], v[194:197], v[124:127]
	v_mfma_f32_16x16x32_bf16 v[112:115], v[86:89], v[208:211], v[112:115]
	v_mfma_f32_16x16x32_bf16 v[108:111], v[94:97], v[208:211], v[108:111]
	v_mfma_f32_16x16x32_bf16 v[78:81], v[86:89], v[218:221], v[78:81]
	v_mfma_f32_16x16x32_bf16 v[74:77], v[94:97], v[218:221], v[74:77]
	s_setprio 0
	s_setprio 1
	v_mfma_f32_16x16x32_bf16 v[136:139], v[162:165], v[178:181], v[136:139]
	v_mfma_f32_16x16x32_bf16 v[132:135], v[170:173], v[178:181], v[132:135]
	v_mfma_f32_16x16x32_bf16 v[120:123], v[162:165], v[190:193], v[120:123]
	v_mfma_f32_16x16x32_bf16 v[116:119], v[170:173], v[190:193], v[116:119]
	v_mfma_f32_16x16x32_bf16 v[104:107], v[162:165], v[204:207], v[104:107]
	v_mfma_f32_16x16x32_bf16 v[100:103], v[170:173], v[204:207], v[100:103]
	v_mfma_f32_16x16x32_bf16 v[70:73], v[162:165], v[214:217], v[70:73]
	v_mfma_f32_16x16x32_bf16 v[66:69], v[170:173], v[214:217], v[66:69]
	v_mfma_f32_16x16x32_bf16 v[136:139], v[166:169], v[182:185], v[136:139]
	v_mfma_f32_16x16x32_bf16 v[132:135], v[174:177], v[182:185], v[132:135]
	v_mfma_f32_16x16x32_bf16 v[120:123], v[166:169], v[194:197], v[120:123]
	v_mfma_f32_16x16x32_bf16 v[116:119], v[174:177], v[194:197], v[116:119]
	v_mfma_f32_16x16x32_bf16 v[104:107], v[166:169], v[208:211], v[104:107]
	v_mfma_f32_16x16x32_bf16 v[100:103], v[174:177], v[208:211], v[100:103]
	v_mfma_f32_16x16x32_bf16 v[70:73], v[166:169], v[218:221], v[70:73]
	v_mfma_f32_16x16x32_bf16 v[66:69], v[174:177], v[218:221], v[66:69]
	s_setprio 0
	s_barrier
	s_add_i32 s46, s53, s9
	v_lshl_add_u64 v[198:199], v[198:199], 0, s[28:29]
	s_mov_b32 m0, s46
	ds_read_b128 v[178:181], v187 offset:49152
	ds_read_b128 v[182:185], v187 offset:50176
	ds_read_b128 v[190:193], v187 offset:51200
	ds_read_b128 v[194:197], v187 offset:52224
	ds_read_b128 v[204:207], v187 offset:53248
	ds_read_b128 v[208:211], v187 offset:54272
	ds_read_b128 v[214:217], v187 offset:55296
	ds_read_b128 v[218:221], v187 offset:56320
	global_load_lds_dwordx4 v[198:199], off
	s_add_i32 m0, s46, 0x2000
	s_add_u32 s44, s44, 0x40080
	v_lshl_add_u64 v[198:199], v[222:223], 0, s[28:29]
	s_addc_u32 s45, s45, 0
	s_add_i32 s46, s54, s9
	global_load_lds_dwordx4 v[198:199], off
	v_lshl_add_u64 v[198:199], s[44:45], 0, v[98:99]
	s_mov_b32 m0, s46
	s_nop 0
	global_load_lds_dwordx4 v[198:199], off
	v_lshl_add_u64 v[198:199], s[44:45], 0, v[152:153]
	s_add_i32 m0, s46, 0x2000
	s_nop 0
	global_load_lds_dwordx4 v[198:199], off
	s_waitcnt vmcnt(6)
	s_waitcnt lgkmcnt(0)
	s_barrier
	s_setprio 1
	s_waitcnt lgkmcnt(0)
	v_mfma_f32_16x16x32_bf16 v[62:65], v[82:85], v[178:181], v[62:65]
	v_mfma_f32_16x16x32_bf16 v[58:61], v[90:93], v[178:181], v[58:61]
	v_mfma_f32_16x16x32_bf16 v[46:49], v[82:85], v[190:193], v[46:49]
	v_mfma_f32_16x16x32_bf16 v[42:45], v[90:93], v[190:193], v[42:45]
	v_mfma_f32_16x16x32_bf16 v[30:33], v[82:85], v[204:207], v[30:33]
	v_mfma_f32_16x16x32_bf16 v[26:29], v[90:93], v[204:207], v[26:29]
	v_mfma_f32_16x16x32_bf16 v[14:17], v[82:85], v[214:217], v[14:17]
	v_mfma_f32_16x16x32_bf16 v[10:13], v[90:93], v[214:217], v[10:13]
	v_mfma_f32_16x16x32_bf16 v[62:65], v[86:89], v[182:185], v[62:65]
	v_mfma_f32_16x16x32_bf16 v[58:61], v[94:97], v[182:185], v[58:61]
	v_mfma_f32_16x16x32_bf16 v[46:49], v[86:89], v[194:197], v[46:49]
	v_mfma_f32_16x16x32_bf16 v[42:45], v[94:97], v[194:197], v[42:45]
	v_mfma_f32_16x16x32_bf16 v[30:33], v[86:89], v[208:211], v[30:33]
	v_mfma_f32_16x16x32_bf16 v[26:29], v[94:97], v[208:211], v[26:29]
	v_mfma_f32_16x16x32_bf16 v[14:17], v[86:89], v[218:221], v[14:17]
	v_mfma_f32_16x16x32_bf16 v[10:13], v[94:97], v[218:221], v[10:13]
	s_setprio 0
	s_setprio 1
	v_mfma_f32_16x16x32_bf16 v[54:57], v[162:165], v[178:181], v[54:57]
	v_mfma_f32_16x16x32_bf16 v[50:53], v[170:173], v[178:181], v[50:53]
	v_mfma_f32_16x16x32_bf16 v[38:41], v[162:165], v[190:193], v[38:41]
	v_mfma_f32_16x16x32_bf16 v[34:37], v[170:173], v[190:193], v[34:37]
	v_mfma_f32_16x16x32_bf16 v[22:25], v[162:165], v[204:207], v[22:25]
	v_mfma_f32_16x16x32_bf16 v[18:21], v[170:173], v[204:207], v[18:21]
	v_mfma_f32_16x16x32_bf16 v[6:9], v[162:165], v[214:217], v[6:9]
	v_mfma_f32_16x16x32_bf16 v[2:5], v[170:173], v[214:217], v[2:5]
	v_mfma_f32_16x16x32_bf16 v[54:57], v[166:169], v[182:185], v[54:57]
	v_mfma_f32_16x16x32_bf16 v[50:53], v[174:177], v[182:185], v[50:53]
	v_mfma_f32_16x16x32_bf16 v[38:41], v[166:169], v[194:197], v[38:41]
	v_mfma_f32_16x16x32_bf16 v[34:37], v[174:177], v[194:197], v[34:37]
	v_mfma_f32_16x16x32_bf16 v[22:25], v[166:169], v[208:211], v[22:25]
	v_mfma_f32_16x16x32_bf16 v[18:21], v[174:177], v[208:211], v[18:21]
	v_mfma_f32_16x16x32_bf16 v[6:9], v[166:169], v[218:221], v[6:9]
	v_mfma_f32_16x16x32_bf16 v[2:5], v[174:177], v[218:221], v[2:5]
	s_setprio 0
	s_barrier
	s_add_i32 s52, s52, 2
	s_add_u32 s42, s42, 0x100
	s_addc_u32 s43, s43, 0
	s_add_u32 s50, s50, 0x100
	s_addc_u32 s51, s51, 0
	s_cmp_gt_u32 s52, 13
	s_cbranch_scc0 .LBB0_1328
	s_and_b64 vcc, exec, s[76:77]
	s_cbranch_vccz .LBB0_1331
	s_barrier
